# branch-GEMM phases: odd workgroups start 10 us late (K-loop of one half overlaps the gate epilogue of the other)
# baseline (speedup 1.0000x reference)
.LBB0_19:
	s_cmp_eq_u32 s0, 4
	s_cbranch_scc1 .Lstag_chk
	s_cmp_eq_u32 s0, 16
	s_cbranch_scc0 .Lstag_done
.Lstag_chk:
	v_readlane_b32 s98, v251, 34
	s_nop 3
	s_and_b32 s98, s98, 1
	s_cmp_eq_u32 s98, 0
	s_cbranch_scc1 .Lstag_done
	s_memrealtime s[98:99]
	s_waitcnt lgkmcnt(0)
	s_mov_b32 s99, s98
.Lstag_spin:
	s_memrealtime s[100:101]
	s_waitcnt lgkmcnt(0)
	s_sub_u32 s100, s100, s99
	s_cmpk_lt_u32 s100, 0x3e8
	s_cbranch_scc1 .Lstag_spin
